# v30 + MLA (mixer C) row-max trees as v_max3-only chains (16 ops instead of 22-24)
# baseline (speedup 1.0000x reference)
.LBB0_159:
	ds_read_b128 v[38:41], v134 offset:6656
	ds_read_b128 v[42:45], v134
	ds_read_b128 v[138:141], v134 offset:32
	ds_read_b128 v[142:145], v134 offset:6688
	s_cmp_eq_u32 s25, -1
	s_cselect_b64 s[18:19], -1, 0
	s_waitcnt lgkmcnt(2)
	v_mfma_f32_32x32x16_bf16 v[54:69], v[42:45], v[70:73], 0
	v_cndmask_b32_e64 v146, -v137, v195, s[18:19]
	v_cmp_lt_i32_e32 vcc, 0, v128
	s_mov_b64 s[20:21], s[18:19]
	v_mfma_f32_32x32x16_bf16 v[38:53], v[38:41], v[70:73], 0
	s_waitcnt lgkmcnt(1)
	v_mfma_f32_32x32x16_bf16 v[54:69], v[138:141], v[74:77], v[54:69]
	s_waitcnt lgkmcnt(0)
	v_mfma_f32_32x32x16_bf16 v[38:53], v[142:145], v[74:77], v[38:53]
	ds_read_b128 v[138:141], v134 offset:64
	ds_read_b128 v[142:145], v134 offset:6720
	s_waitcnt lgkmcnt(1)
	v_mfma_f32_32x32x16_bf16 v[54:69], v[138:141], v[78:81], v[54:69]
	s_waitcnt lgkmcnt(0)
	v_mfma_f32_32x32x16_bf16 v[38:53], v[142:145], v[78:81], v[38:53]
	ds_read_b128 v[138:141], v134 offset:96
	ds_read_b128 v[142:145], v134 offset:6752
	s_waitcnt lgkmcnt(1)
	v_mfma_f32_32x32x16_bf16 v[54:69], v[138:141], v[82:85], v[54:69]
	s_waitcnt lgkmcnt(0)
	v_mfma_f32_32x32x16_bf16 v[38:53], v[142:145], v[82:85], v[38:53]
	ds_read_b128 v[138:141], v134 offset:128
	ds_read_b128 v[142:145], v134 offset:6784
	s_waitcnt lgkmcnt(1)
	v_mfma_f32_32x32x16_bf16 v[54:69], v[138:141], v[86:89], v[54:69]
	s_waitcnt lgkmcnt(0)
	v_mfma_f32_32x32x16_bf16 v[38:53], v[142:145], v[86:89], v[38:53]
	ds_read_b128 v[138:141], v134 offset:160
	ds_read_b128 v[142:145], v134 offset:6816
	s_waitcnt lgkmcnt(1)
	v_mfma_f32_32x32x16_bf16 v[54:69], v[138:141], v[90:93], v[54:69]
	s_waitcnt lgkmcnt(0)
	v_mfma_f32_32x32x16_bf16 v[38:53], v[142:145], v[90:93], v[38:53]
	s_nop 9
	v_fma_f32 v0, v54, s88, v146
	v_fma_f32 v1, v55, s88, v146
	v_cndmask_b32_e32 v4, v196, v1, vcc
	v_cmp_lt_i32_e32 vcc, -1, v128
	s_nop 1
	v_cndmask_b32_e32 v143, v196, v0, vcc
	v_pk_fma_f32 v[0:1], v[38:39], s[88:89], v[146:147] op_sel_hi:[1,0,0]
	v_cmp_lt_i32_e32 vcc, 32, v128
	s_nop 1
	v_cndmask_b32_e32 v142, v196, v1, vcc
	v_cmp_lt_i32_e32 vcc, 31, v128
	s_nop 1
	v_cndmask_b32_e32 v145, v196, v0, vcc
	v_pk_fma_f32 v[0:1], v[56:57], s[88:89], v[146:147] op_sel_hi:[1,0,0]
	v_cmp_lt_i32_e32 vcc, 2, v128
	s_nop 1
	v_cndmask_b32_e32 v130, v196, v1, vcc
	v_cmp_lt_i32_e32 vcc, 1, v128
	s_nop 1
	v_cndmask_b32_e32 v140, v196, v0, vcc
	v_pk_fma_f32 v[0:1], v[40:41], s[88:89], v[146:147] op_sel_hi:[1,0,0]
	v_cmp_lt_i32_e32 vcc, 34, v128
	s_nop 1
	v_cndmask_b32_e32 v139, v196, v1, vcc
	v_cmp_lt_i32_e32 vcc, 33, v128
	s_nop 1
	v_cndmask_b32_e32 v144, v196, v0, vcc
	v_pk_fma_f32 v[0:1], v[58:59], s[88:89], v[146:147] op_sel_hi:[1,0,0]
	v_cmp_lt_i32_e32 vcc, 8, v128
	s_nop 1
	v_cndmask_b32_e32 v56, v196, v1, vcc
	v_cmp_lt_i32_e32 vcc, 7, v128
	s_nop 1
	v_cndmask_b32_e32 v138, v196, v0, vcc
	v_pk_fma_f32 v[0:1], v[42:43], s[88:89], v[146:147] op_sel_hi:[1,0,0]
	v_cmp_lt_i32_e32 vcc, 40, v128
	s_nop 1
	v_cndmask_b32_e32 v131, v196, v1, vcc
	v_cmp_lt_i32_e32 vcc, 39, v128
	s_nop 1
	v_cndmask_b32_e32 v141, v196, v0, vcc
	v_pk_fma_f32 v[0:1], v[60:61], s[88:89], v[146:147] op_sel_hi:[1,0,0]
	v_cmp_lt_i32_e32 vcc, 10, v128
	s_nop 1
	v_cndmask_b32_e32 v54, v196, v1, vcc
	v_cmp_lt_i32_e32 vcc, 9, v128
	s_nop 1
	v_cndmask_b32_e32 v58, v196, v0, vcc
	v_pk_fma_f32 v[0:1], v[44:45], s[88:89], v[146:147] op_sel_hi:[1,0,0]
	v_cmp_lt_i32_e32 vcc, 42, v128
	s_nop 1
	v_cndmask_b32_e32 v57, v196, v1, vcc
	v_cmp_lt_i32_e32 vcc, 41, v128
	s_nop 1
	v_cndmask_b32_e32 v60, v196, v0, vcc
	v_pk_fma_f32 v[0:1], v[62:63], s[88:89], v[146:147] op_sel_hi:[1,0,0]
	v_cmp_lt_i32_e32 vcc, 16, v128
	s_nop 1
	v_cndmask_b32_e32 v43, v196, v1, vcc
	v_cmp_lt_i32_e32 vcc, 15, v128
	s_nop 1
	v_cndmask_b32_e32 v55, v196, v0, vcc
	v_pk_fma_f32 v[0:1], v[46:47], s[88:89], v[146:147] op_sel_hi:[1,0,0]
	v_cmp_lt_i32_e32 vcc, 48, v128
	s_nop 1
	v_cndmask_b32_e32 v47, v196, v1, vcc
	v_cmp_lt_i32_e32 vcc, 47, v128
	s_nop 1
	v_cndmask_b32_e32 v59, v196, v0, vcc
	v_pk_fma_f32 v[0:1], v[64:65], s[88:89], v[146:147] op_sel_hi:[1,0,0]
	v_cmp_lt_i32_e32 vcc, 18, v128
	s_nop 1
	v_cndmask_b32_e32 v39, v196, v1, vcc
	v_cmp_lt_i32_e32 vcc, 17, v128
	s_nop 1
	v_cndmask_b32_e32 v45, v196, v0, vcc
	v_pk_fma_f32 v[0:1], v[48:49], s[88:89], v[146:147] op_sel_hi:[1,0,0]
	v_cmp_lt_i32_e32 vcc, 50, v128
	v_max_f32_e32 v49, v4, v142
	v_max3_f32 v49, v143, v145, v49
	v_cndmask_b32_e32 v44, v196, v1, vcc
	v_cmp_lt_i32_e32 vcc, 49, v128
	s_nop 1
	v_cndmask_b32_e32 v48, v196, v0, vcc
	v_pk_fma_f32 v[0:1], v[66:67], s[88:89], v[146:147] op_sel_hi:[1,0,0]
	v_cmp_lt_i32_e32 vcc, 24, v128
	s_nop 1
	v_cndmask_b32_e32 v3, v196, v1, vcc
	v_cmp_lt_i32_e32 vcc, 23, v128
	s_nop 1
	v_cndmask_b32_e32 v41, v196, v0, vcc
	v_pk_fma_f32 v[0:1], v[50:51], s[88:89], v[146:147] op_sel_hi:[1,0,0]
	v_cmp_lt_i32_e32 vcc, 56, v128
	v_pk_fma_f32 v[50:51], v[68:69], s[88:89], v[146:147] op_sel_hi:[1,0,0]
	s_nop 0
	v_cndmask_b32_e32 v40, v196, v1, vcc
	v_cmp_lt_i32_e32 vcc, 55, v128
	s_nop 1
	v_cndmask_b32_e32 v46, v196, v0, vcc
	v_cmp_lt_i32_e32 vcc, 26, v128
	s_nop 1
	v_cndmask_b32_e32 v0, v196, v51, vcc
	v_cmp_lt_i32_e32 vcc, 25, v128
	s_nop 1
	v_cndmask_b32_e32 v38, v196, v50, vcc
	v_pk_fma_f32 v[50:51], v[52:53], s[88:89], v[146:147] op_sel_hi:[1,0,0]
	v_cmp_lt_i32_e32 vcc, 58, v128
	s_nop 1
	v_cndmask_b32_e32 v1, v196, v51, vcc
	v_cmp_lt_i32_e32 vcc, 57, v128
	v_max_f32_e32 v51, v130, v139
	s_nop 0
	v_cndmask_b32_e32 v42, v196, v50, vcc
	v_max3_f32 v50, v140, v144, v51
	v_max3_f32 v49, v49, v138, v141
	v_max3_f32 v50, v50, v56, v131
	v_max3_f32 v49, v49, v58, v60
	v_max3_f32 v50, v50, v54, v57
	v_max3_f32 v49, v49, v55, v59
	v_max3_f32 v50, v50, v43, v47
	v_max3_f32 v49, v49, v45, v48
	v_max3_f32 v50, v50, v39, v44
	v_max3_f32 v49, v49, v41, v46
	v_max3_f32 v50, v50, v3, v40
	v_max3_f32 v49, v49, v38, v42
	v_max3_f32 v50, v50, v0, v1
	v_max_f32_e32 v49, v49, v50
	v_mov_b32_e32 v50, v49
	s_and_b64 vcc, exec, s[18:19]
	s_waitcnt lgkmcnt(0)
	s_nop 1
	v_permlane32_swap_b32_e32 v50, v49
	v_max_f32_e32 v49, v49, v50
	v_cmp_lt_f32_e64 s[46:47], s38, v49
	s_cbranch_vccnz .LBB0_161
	s_cmp_lg_u64 s[46:47], 0
	s_cselect_b64 s[20:21], -1, 0

.LBB0_173:
	ds_read_b128 v[0:3], v134 offset:19968
	ds_read_b128 v[38:41], v134 offset:13312
	ds_read_b128 v[138:141], v134 offset:13344
	s_cmp_eq_u32 s25, 0
	s_cselect_b64 s[18:19], -1, 0
	v_add_u32_e32 v147, 64, v128
	s_waitcnt lgkmcnt(1)
	v_mfma_f32_32x32x16_bf16 v[54:69], v[38:41], v[70:73], 0
	v_cndmask_b32_e64 v146, -v137, v195, s[18:19]
	v_cmp_lt_i32_e32 vcc, 0, v147
	s_mov_b64 s[20:21], s[18:19]
	v_mfma_f32_32x32x16_bf16 v[38:53], v[0:3], v[70:73], 0
	ds_read_b128 v[0:3], v134 offset:20000
	s_waitcnt lgkmcnt(1)
	v_mfma_f32_32x32x16_bf16 v[54:69], v[138:141], v[74:77], v[54:69]
	s_waitcnt lgkmcnt(0)
	v_mfma_f32_32x32x16_bf16 v[38:53], v[0:3], v[74:77], v[38:53]
	ds_read_b128 v[0:3], v134 offset:13376
	ds_read_b128 v[138:141], v134 offset:20032
	s_waitcnt lgkmcnt(1)
	v_mfma_f32_32x32x16_bf16 v[54:69], v[0:3], v[78:81], v[54:69]
	s_waitcnt lgkmcnt(0)
	v_mfma_f32_32x32x16_bf16 v[38:53], v[138:141], v[78:81], v[38:53]
	ds_read_b128 v[0:3], v134 offset:13408
	ds_read_b128 v[138:141], v134 offset:20064
	s_waitcnt lgkmcnt(1)
	v_mfma_f32_32x32x16_bf16 v[54:69], v[0:3], v[82:85], v[54:69]
	s_waitcnt lgkmcnt(0)
	v_mfma_f32_32x32x16_bf16 v[38:53], v[138:141], v[82:85], v[38:53]
	ds_read_b128 v[0:3], v134 offset:13440
	ds_read_b128 v[138:141], v134 offset:20096
	s_waitcnt lgkmcnt(1)
	v_mfma_f32_32x32x16_bf16 v[54:69], v[0:3], v[86:89], v[54:69]
	s_waitcnt lgkmcnt(0)
	v_mfma_f32_32x32x16_bf16 v[38:53], v[138:141], v[86:89], v[38:53]
	ds_read_b128 v[0:3], v134 offset:13472
	ds_read_b128 v[138:141], v134 offset:20128
	s_waitcnt lgkmcnt(1)
	v_mfma_f32_32x32x16_bf16 v[54:69], v[0:3], v[90:93], v[54:69]
	s_waitcnt lgkmcnt(0)
	v_mfma_f32_32x32x16_bf16 v[38:53], v[138:141], v[90:93], v[38:53]
	s_nop 9
	v_fma_f32 v0, v54, s88, v146
	v_fma_f32 v1, v55, s88, v146
	v_cndmask_b32_e32 v4, v196, v1, vcc
	v_cmp_lt_i32_e32 vcc, -1, v147
	s_nop 1
	v_cndmask_b32_e32 v143, v196, v0, vcc
	v_pk_fma_f32 v[0:1], v[38:39], s[88:89], v[146:147] op_sel_hi:[1,0,0]
	v_cmp_lt_i32_e32 vcc, 32, v147
	s_nop 1
	v_cndmask_b32_e32 v142, v196, v1, vcc
	v_cmp_lt_i32_e32 vcc, 31, v147
	s_nop 1
	v_cndmask_b32_e32 v145, v196, v0, vcc
	v_pk_fma_f32 v[0:1], v[56:57], s[88:89], v[146:147] op_sel_hi:[1,0,0]
	v_cmp_lt_i32_e32 vcc, 2, v147
	s_nop 1
	v_cndmask_b32_e32 v130, v196, v1, vcc
	v_cmp_lt_i32_e32 vcc, 1, v147
	s_nop 1
	v_cndmask_b32_e32 v140, v196, v0, vcc
	v_pk_fma_f32 v[0:1], v[40:41], s[88:89], v[146:147] op_sel_hi:[1,0,0]
	v_cmp_lt_i32_e32 vcc, 34, v147
	s_nop 1
	v_cndmask_b32_e32 v139, v196, v1, vcc
	v_cmp_lt_i32_e32 vcc, 33, v147
	s_nop 1
	v_cndmask_b32_e32 v144, v196, v0, vcc
	v_pk_fma_f32 v[0:1], v[58:59], s[88:89], v[146:147] op_sel_hi:[1,0,0]
	v_cmp_lt_i32_e32 vcc, 8, v147
	s_nop 1
	v_cndmask_b32_e32 v56, v196, v1, vcc
	v_cmp_lt_i32_e32 vcc, 7, v147
	s_nop 1
	v_cndmask_b32_e32 v138, v196, v0, vcc
	v_pk_fma_f32 v[0:1], v[42:43], s[88:89], v[146:147] op_sel_hi:[1,0,0]
	v_cmp_lt_i32_e32 vcc, 40, v147
	s_nop 1
	v_cndmask_b32_e32 v131, v196, v1, vcc
	v_cmp_lt_i32_e32 vcc, 39, v147
	s_nop 1
	v_cndmask_b32_e32 v141, v196, v0, vcc
	v_pk_fma_f32 v[0:1], v[60:61], s[88:89], v[146:147] op_sel_hi:[1,0,0]
	v_cmp_lt_i32_e32 vcc, 10, v147
	s_nop 1
	v_cndmask_b32_e32 v54, v196, v1, vcc
	v_cmp_lt_i32_e32 vcc, 9, v147
	s_nop 1
	v_cndmask_b32_e32 v58, v196, v0, vcc
	v_pk_fma_f32 v[0:1], v[44:45], s[88:89], v[146:147] op_sel_hi:[1,0,0]
	v_cmp_lt_i32_e32 vcc, 42, v147
	s_nop 1
	v_cndmask_b32_e32 v57, v196, v1, vcc
	v_cmp_lt_i32_e32 vcc, 41, v147
	s_nop 1
	v_cndmask_b32_e32 v60, v196, v0, vcc
	v_pk_fma_f32 v[0:1], v[62:63], s[88:89], v[146:147] op_sel_hi:[1,0,0]
	v_cmp_lt_i32_e32 vcc, 16, v147
	s_nop 1
	v_cndmask_b32_e32 v42, v196, v1, vcc
	v_cmp_lt_i32_e32 vcc, 15, v147
	s_nop 1
	v_cndmask_b32_e32 v55, v196, v0, vcc
	v_pk_fma_f32 v[0:1], v[46:47], s[88:89], v[146:147] op_sel_hi:[1,0,0]
	v_cmp_lt_i32_e32 vcc, 48, v147
	s_nop 1
	v_cndmask_b32_e32 v46, v196, v1, vcc
	v_cmp_lt_i32_e32 vcc, 47, v147
	s_nop 1
	v_cndmask_b32_e32 v59, v196, v0, vcc
	v_pk_fma_f32 v[0:1], v[64:65], s[88:89], v[146:147] op_sel_hi:[1,0,0]
	v_cmp_lt_i32_e32 vcc, 18, v147
	s_nop 1
	v_cndmask_b32_e32 v38, v196, v1, vcc
	v_cmp_lt_i32_e32 vcc, 17, v147
	s_nop 1
	v_cndmask_b32_e32 v44, v196, v0, vcc
	v_pk_fma_f32 v[0:1], v[48:49], s[88:89], v[146:147] op_sel_hi:[1,0,0]
	v_cmp_lt_i32_e32 vcc, 50, v147
	v_pk_fma_f32 v[48:49], v[68:69], s[88:89], v[146:147] op_sel_hi:[1,0,0]
	s_nop 0
	v_cndmask_b32_e32 v43, v196, v1, vcc
	v_cmp_lt_i32_e32 vcc, 49, v147
	s_nop 1
	v_cndmask_b32_e32 v47, v196, v0, vcc
	v_pk_fma_f32 v[0:1], v[66:67], s[88:89], v[146:147] op_sel_hi:[1,0,0]
	v_cmp_lt_i32_e32 vcc, 24, v147
	s_nop 1
	v_cndmask_b32_e32 v2, v196, v1, vcc
	v_cmp_lt_i32_e32 vcc, 23, v147
	s_nop 1
	v_cndmask_b32_e32 v40, v196, v0, vcc
	v_pk_fma_f32 v[0:1], v[50:51], s[88:89], v[146:147] op_sel_hi:[1,0,0]
	v_cmp_lt_i32_e32 vcc, 56, v147
	v_max_f32_e32 v50, v130, v139
	s_nop 0
	v_cndmask_b32_e32 v39, v196, v1, vcc
	v_cmp_lt_i32_e32 vcc, 55, v147
	s_nop 1
	v_cndmask_b32_e32 v45, v196, v0, vcc
	v_cmp_lt_i32_e32 vcc, 26, v147
	s_nop 1
	v_cndmask_b32_e32 v0, v196, v49, vcc
	v_cmp_lt_i32_e32 vcc, 25, v147
	s_nop 1
	v_cndmask_b32_e32 v3, v196, v48, vcc
	v_pk_fma_f32 v[48:49], v[52:53], s[88:89], v[146:147] op_sel_hi:[1,0,0]
	v_cmp_lt_i32_e32 vcc, 58, v147
	s_nop 1
	v_cndmask_b32_e32 v1, v196, v49, vcc
	v_cmp_lt_i32_e32 vcc, 57, v147
	v_max_f32_e32 v49, v140, v144
	s_nop 0
	v_cndmask_b32_e32 v41, v196, v48, vcc
	v_max3_f32 v48, v4, v142, v143
	v_max3_f32 v49, v145, v49, v50
	v_max3_f32 v48, v48, v138, v141
	v_max3_f32 v49, v49, v56, v131
	v_max3_f32 v48, v48, v58, v60
	v_max3_f32 v49, v49, v54, v57
	v_max3_f32 v48, v48, v55, v59
	v_max3_f32 v49, v49, v42, v46
	v_max3_f32 v48, v48, v44, v47
	v_max3_f32 v49, v49, v38, v43
	v_max3_f32 v48, v48, v40, v45
	v_max3_f32 v49, v49, v2, v39
	v_max3_f32 v48, v48, v3, v41
	v_max3_f32 v49, v49, v0, v1
	v_max_f32_e32 v48, v48, v49
	v_mov_b32_e32 v49, v48
	s_and_b64 vcc, exec, s[18:19]
	s_waitcnt lgkmcnt(0)
	s_nop 1
	v_permlane32_swap_b32_e32 v49, v48
	v_max_f32_e32 v48, v48, v49
	v_cmp_lt_f32_e64 s[46:47], s38, v48
	s_cbranch_vccnz .LBB0_175
	s_cmp_lg_u64 s[46:47], 0
	s_cselect_b64 s[20:21], -1, 0

.LBB0_194:
	v_add_u32_e32 v3, s4, v134
	ds_read_b128 v[38:41], v3 offset:6656
	ds_read_b128 v[42:45], v3
	ds_read_b128 v[120:123], v3 offset:32
	ds_read_b128 v[124:127], v3 offset:6688
	ds_read_b128 v[204:207], v3 offset:64
	ds_read_b128 v[208:211], v3 offset:6720
	ds_read_b128 v[212:215], v3 offset:96
	ds_read_b128 v[216:219], v3 offset:6752
	ds_read_b128 v[220:223], v3 offset:128
	ds_read_b128 v[224:227], v3 offset:6784
	ds_read_b128 v[228:231], v3 offset:160
	ds_read_b128 v[232:235], v3 offset:6816
	s_cmp_eq_u32 s7, s23
	s_cselect_b64 s[18:19], -1, 0
	s_waitcnt lgkmcnt(10)
	v_mfma_f32_32x32x16_bf16 v[54:69], v[42:45], v[70:73], 0
	v_cndmask_b32_e64 v4, -v137, v195, s[18:19]
	s_and_b64 vcc, exec, s[18:19]
	s_mov_b64 s[20:21], s[18:19]
	v_mfma_f32_32x32x16_bf16 v[38:53], v[38:41], v[70:73], 0
	s_waitcnt lgkmcnt(9)
	v_mfma_f32_32x32x16_bf16 v[54:69], v[120:123], v[74:77], v[54:69]
	s_waitcnt lgkmcnt(8)
	v_mfma_f32_32x32x16_bf16 v[38:53], v[124:127], v[74:77], v[38:53]
	s_waitcnt lgkmcnt(7)
	v_mfma_f32_32x32x16_bf16 v[54:69], v[204:207], v[78:81], v[54:69]
	s_waitcnt lgkmcnt(6)
	v_mfma_f32_32x32x16_bf16 v[38:53], v[208:211], v[78:81], v[38:53]
	s_waitcnt lgkmcnt(5)
	v_mfma_f32_32x32x16_bf16 v[54:69], v[212:215], v[82:85], v[54:69]
	s_waitcnt lgkmcnt(4)
	v_mfma_f32_32x32x16_bf16 v[38:53], v[216:219], v[82:85], v[38:53]
	s_waitcnt lgkmcnt(3)
	v_mfma_f32_32x32x16_bf16 v[54:69], v[220:223], v[86:89], v[54:69]
	s_waitcnt lgkmcnt(2)
	v_mfma_f32_32x32x16_bf16 v[38:53], v[224:227], v[86:89], v[38:53]
	s_waitcnt lgkmcnt(1)
	v_mfma_f32_32x32x16_bf16 v[54:69], v[228:231], v[90:93], v[54:69]
	s_waitcnt lgkmcnt(0)
	v_mfma_f32_32x32x16_bf16 v[38:53], v[232:235], v[90:93], v[38:53]
	s_nop 9
	v_fma_f32 v128, v54, s88, v4
	v_fma_f32 v129, v55, s88, v4
	v_fma_f32 v124, v56, s88, v4
	v_fma_f32 v125, v57, s88, v4
	v_fma_f32 v120, v58, s88, v4
	v_fma_f32 v121, v59, s88, v4
	v_pk_fma_f32 v[58:59], v[60:61], s[88:89], v[4:5] op_sel_hi:[1,0,0]
	v_pk_fma_f32 v[54:55], v[62:63], s[88:89], v[4:5] op_sel_hi:[1,0,0]
	v_pk_fma_f32 v[130:131], v[38:39], s[88:89], v[4:5] op_sel_hi:[1,0,0]
	v_pk_fma_f32 v[126:127], v[40:41], s[88:89], v[4:5] op_sel_hi:[1,0,0]
	v_max_f32_e32 v3, v129, v131
	v_pk_fma_f32 v[122:123], v[42:43], s[88:89], v[4:5] op_sel_hi:[1,0,0]
	v_pk_fma_f32 v[60:61], v[44:45], s[88:89], v[4:5] op_sel_hi:[1,0,0]
	v_pk_fma_f32 v[56:57], v[46:47], s[88:89], v[4:5] op_sel_hi:[1,0,0]
	v_pk_fma_f32 v[46:47], v[64:65], s[88:89], v[4:5] op_sel_hi:[1,0,0]
	v_pk_fma_f32 v[48:49], v[48:49], s[88:89], v[4:5] op_sel_hi:[1,0,0]
	v_pk_fma_f32 v[42:43], v[66:67], s[88:89], v[4:5] op_sel_hi:[1,0,0]
	v_pk_fma_f32 v[44:45], v[50:51], s[88:89], v[4:5] op_sel_hi:[1,0,0]
	v_pk_fma_f32 v[38:39], v[68:69], s[88:89], v[4:5] op_sel_hi:[1,0,0]
	v_pk_fma_f32 v[40:41], v[52:53], s[88:89], v[4:5] op_sel_hi:[1,0,0]
	v_max3_f32 v4, v128, v130, v124
	v_max3_f32 v3, v3, v126, v125
	v_max3_f32 v4, v4, v127, v120
	v_max3_f32 v3, v3, v122, v121
	v_max3_f32 v4, v4, v123, v58
	v_max3_f32 v3, v3, v60, v59
	v_max3_f32 v4, v4, v61, v54
	v_max3_f32 v3, v3, v56, v55
	v_max3_f32 v4, v4, v57, v46
	v_max3_f32 v3, v3, v48, v47
	v_max3_f32 v4, v4, v49, v42
	v_max3_f32 v3, v3, v44, v43
	v_max3_f32 v4, v4, v45, v38
	v_max3_f32 v3, v3, v40, v39
	v_max_f32_e32 v4, v4, v41
	v_max_f32_e32 v3, v3, v4
	v_mov_b32_e32 v4, v3
	s_waitcnt lgkmcnt(0)
	s_nop 1
	v_permlane32_swap_b32_e32 v4, v3
	v_max_f32_e32 v3, v3, v4
	v_cmp_lt_f32_e64 s[46:47], s38, v3
	s_cbranch_vccnz .LBB0_196
	s_cmp_lg_u64 s[46:47], 0
	s_cselect_b64 s[20:21], -1, 0

.LBB0_208:
	v_add_u32_e32 v3, s22, v134
	ds_read_b128 v[38:41], v3 offset:6656
	ds_read_b128 v[42:45], v3
	ds_read_b128 v[120:123], v3 offset:32
	ds_read_b128 v[124:127], v3 offset:6688
	ds_read_b128 v[204:207], v3 offset:64
	ds_read_b128 v[208:211], v3 offset:6720
	ds_read_b128 v[212:215], v3 offset:96
	ds_read_b128 v[216:219], v3 offset:6752
	ds_read_b128 v[220:223], v3 offset:128
	ds_read_b128 v[224:227], v3 offset:6784
	ds_read_b128 v[228:231], v3 offset:160
	ds_read_b128 v[232:235], v3 offset:6816
	s_cmp_eq_u32 s25, s23
	s_cselect_b64 s[18:19], -1, 0
	s_waitcnt lgkmcnt(10)
	v_mfma_f32_32x32x16_bf16 v[54:69], v[42:45], v[70:73], 0
	v_cndmask_b32_e64 v4, -v137, v195, s[18:19]
	s_and_b64 vcc, exec, s[18:19]
	s_mov_b64 s[20:21], s[18:19]
	v_mfma_f32_32x32x16_bf16 v[38:53], v[38:41], v[70:73], 0
	s_waitcnt lgkmcnt(9)
	v_mfma_f32_32x32x16_bf16 v[54:69], v[120:123], v[74:77], v[54:69]
	s_waitcnt lgkmcnt(8)
	v_mfma_f32_32x32x16_bf16 v[38:53], v[124:127], v[74:77], v[38:53]
	s_waitcnt lgkmcnt(7)
	v_mfma_f32_32x32x16_bf16 v[54:69], v[204:207], v[78:81], v[54:69]
	s_waitcnt lgkmcnt(6)
	v_mfma_f32_32x32x16_bf16 v[38:53], v[208:211], v[78:81], v[38:53]
	s_waitcnt lgkmcnt(5)
	v_mfma_f32_32x32x16_bf16 v[54:69], v[212:215], v[82:85], v[54:69]
	s_waitcnt lgkmcnt(4)
	v_mfma_f32_32x32x16_bf16 v[38:53], v[216:219], v[82:85], v[38:53]
	s_waitcnt lgkmcnt(3)
	v_mfma_f32_32x32x16_bf16 v[54:69], v[220:223], v[86:89], v[54:69]
	s_waitcnt lgkmcnt(2)
	v_mfma_f32_32x32x16_bf16 v[38:53], v[224:227], v[86:89], v[38:53]
	s_waitcnt lgkmcnt(1)
	v_mfma_f32_32x32x16_bf16 v[54:69], v[228:231], v[90:93], v[54:69]
	s_waitcnt lgkmcnt(0)
	v_mfma_f32_32x32x16_bf16 v[38:53], v[232:235], v[90:93], v[38:53]
	s_nop 9
	v_fma_f32 v128, v54, s88, v4
	v_fma_f32 v129, v55, s88, v4
	v_fma_f32 v124, v56, s88, v4
	v_fma_f32 v125, v57, s88, v4
	v_fma_f32 v120, v58, s88, v4
	v_fma_f32 v121, v59, s88, v4
	v_pk_fma_f32 v[58:59], v[60:61], s[88:89], v[4:5] op_sel_hi:[1,0,0]
	v_pk_fma_f32 v[54:55], v[62:63], s[88:89], v[4:5] op_sel_hi:[1,0,0]
	v_pk_fma_f32 v[130:131], v[38:39], s[88:89], v[4:5] op_sel_hi:[1,0,0]
	v_pk_fma_f32 v[126:127], v[40:41], s[88:89], v[4:5] op_sel_hi:[1,0,0]
	v_max_f32_e32 v3, v129, v131
	v_pk_fma_f32 v[122:123], v[42:43], s[88:89], v[4:5] op_sel_hi:[1,0,0]
	v_pk_fma_f32 v[60:61], v[44:45], s[88:89], v[4:5] op_sel_hi:[1,0,0]
	v_pk_fma_f32 v[56:57], v[46:47], s[88:89], v[4:5] op_sel_hi:[1,0,0]
	v_pk_fma_f32 v[46:47], v[64:65], s[88:89], v[4:5] op_sel_hi:[1,0,0]
	v_pk_fma_f32 v[48:49], v[48:49], s[88:89], v[4:5] op_sel_hi:[1,0,0]
	v_pk_fma_f32 v[42:43], v[66:67], s[88:89], v[4:5] op_sel_hi:[1,0,0]
	v_pk_fma_f32 v[44:45], v[50:51], s[88:89], v[4:5] op_sel_hi:[1,0,0]
	v_pk_fma_f32 v[38:39], v[68:69], s[88:89], v[4:5] op_sel_hi:[1,0,0]
	v_pk_fma_f32 v[40:41], v[52:53], s[88:89], v[4:5] op_sel_hi:[1,0,0]
	v_max3_f32 v4, v128, v130, v124
	v_max3_f32 v3, v3, v126, v125
	v_max3_f32 v4, v4, v127, v120
	v_max3_f32 v3, v3, v122, v121
	v_max3_f32 v4, v4, v123, v58
	v_max3_f32 v3, v3, v60, v59
	v_max3_f32 v4, v4, v61, v54
	v_max3_f32 v3, v3, v56, v55
	v_max3_f32 v4, v4, v57, v46
	v_max3_f32 v3, v3, v48, v47
	v_max3_f32 v4, v4, v49, v42
	v_max3_f32 v3, v3, v44, v43
	v_max3_f32 v4, v4, v45, v38
	v_max3_f32 v3, v3, v40, v39
	v_max_f32_e32 v4, v4, v41
	v_max_f32_e32 v3, v3, v4
	v_mov_b32_e32 v4, v3
	s_waitcnt lgkmcnt(0)
	s_nop 1
	v_permlane32_swap_b32_e32 v4, v3
	v_max_f32_e32 v3, v3, v4
	v_cmp_lt_f32_e64 s[46:47], s38, v3
	s_cbranch_vccnz .LBB0_210
	s_cmp_lg_u64 s[46:47], 0
	s_cselect_b64 s[20:21], -1, 0
